# conversion slices placed before each staging-loop barrier (pending half tile finished, next loads issued as the youngest operations; the stagers' 10-load blocks are left in flight through a counted wa
# speedup vs baseline: 1.0022x; 1.0022x over previous
; #define GAS __attribute__((address_space(1)))
;     __device__ __forceinline__ void ids() { lane = fresh_lane(); tid = wave * 64 + lane; }
; __device__ __forceinline__ void rwkv_scan_phase(Frame& F, const bf16* RKV, const float* WAG, const bf16* AGB, const float* k_k, const float* k_a, const float* r_k, bf16* Y, float* BS, float* ST2) {
;     F.ids();
;     const int tid = F.tid, lane = F.lane, wave = F.wave;
;     for (int item = F.vcu; item < NB * 32 * 2; item += F.G) {
;         const int half = item & 1, h = (item >> 1) & 31, b = item >> 6;
;         const size_t gbase = (size_t)b * SEQ * D + h * 64;
;         __syncthreads();
;         if (wave >= 4) {
;             const int st = tid - 256, ts = st >> 4, c4 = st & 15;
;             const f32x4 kkc = *(const GAS f32x4*)(k_k + h * 64 + 4 * c4), kac = *(const GAS f32x4*)(k_a + h * 64 + 4 * c4), rkc = *(const GAS f32x4*)(r_k + h * 64 + 4 * c4);
;     ...
;             constexpr int NCH = SEQ / SC_T;
;             v2u RAh[2][4], RBh[2][4]; f32x4 RAw[2], RBw[2];
;             ST_LOAD(RA, 0); ST_LOAD(RB, 1);
;             ST_PROC(RA, 0);
.LBB0_1758:
	s_mul_i32 s70, s52, 3
	s_mul_i32 s65, s96, 3
	s_add_u32 s65, s65, s80
	s_sub_u32 s65, s65, 5
	s_sub_u32 s65, s65, s70
	s_mov_b32 s66, 1
	s_mov_b32 s67, 0
	s_mov_b32 s68, 0
	s_mov_b32 s69, 0
	s_mov_b32 s71, 0
	s_mov_b32 s32, 0
	s_ashr_i32 s48, s55, 6
	s_bfe_u32 s6, s55, 0x50001
	s_ashr_i32 s49, s48, 31
	s_lshl_b64 s[44:45], s[48:49], 22
	s_lshl_b32 s0, s6, 6
	s_or_b32 s44, s44, s0
	s_waitcnt vmcnt(5)
	v_mov_b32_e32 v61, s45
	v_or_b32_e32 v60, s44, v90
	v_lshl_add_u64 v[12:13], v[60:61], 0, v[108:109]
	v_lshlrev_b64 v[14:15], 1, v[12:13]
	s_lshl_b32 s0, s6, 8
	v_lshl_add_u64 v[16:17], s[12:13], 0, v[14:15]
	v_lshl_add_u64 v[0:1], v[94:95], 0, s[0:1]
	v_lshl_add_u64 v[4:5], v[96:97], 0, s[0:1]
	v_lshl_add_u64 v[8:9], v[98:99], 0, s[0:1]
	global_load_dwordx2 v[30:31], v[16:17], off
	v_lshl_add_u64 v[16:17], s[24:25], 0, v[14:15]
	v_lshl_add_u64 v[18:19], s[26:27], 0, v[14:15]
	v_lshl_add_u64 v[12:13], v[12:13], 2, s[14:15]
	global_load_dwordx4 v[0:3], v[0:1], off
	v_lshl_add_u64 v[14:15], s[16:17], 0, v[14:15]
	global_load_dwordx4 v[4:7], v[4:5], off
	s_and_b32 s0, s55, 1
	global_load_dwordx4 v[8:11], v[8:9], off
	s_nop 0
	global_load_dwordx2 v[32:33], v[16:17], off
	global_load_dwordx2 v[42:43], v[18:19], off
	s_nop 0
	global_load_dwordx4 v[16:19], v[12:13], off
	global_load_dwordx2 v[34:35], v[14:15], off
	v_lshl_add_u64 v[12:13], v[60:61], 0, v[112:113]
	v_lshlrev_b64 v[14:15], 1, v[12:13]
	v_lshl_add_u64 v[20:21], s[12:13], 0, v[14:15]
	global_load_dwordx2 v[38:39], v[20:21], off
	v_lshl_add_u64 v[20:21], s[24:25], 0, v[14:15]
	v_lshl_add_u64 v[22:23], s[26:27], 0, v[14:15]
	global_load_dwordx2 v[40:41], v[20:21], off
	global_load_dwordx2 v[36:37], v[22:23], off
	v_lshl_add_u64 v[12:13], v[12:13], 2, s[14:15]
	v_lshl_add_u64 v[20:21], s[16:17], 0, v[14:15]
	global_load_dwordx4 v[12:15], v[12:13], off
	s_nop 0
	global_load_dwordx2 v[44:45], v[20:21], off
	v_lshl_add_u64 v[20:21], v[60:61], 0, v[114:115]
	v_lshlrev_b64 v[22:23], 1, v[20:21]
	s_waitcnt vmcnt(15)
	v_lshl_add_u64 v[24:25], s[12:13], 0, v[22:23]
	global_load_dwordx2 v[64:65], v[24:25], off
	v_lshl_add_u64 v[24:25], s[24:25], 0, v[22:23]
	v_lshl_add_u64 v[26:27], s[26:27], 0, v[22:23]
	v_lshl_add_u64 v[20:21], v[20:21], 2, s[14:15]
	global_load_dwordx2 v[66:67], v[24:25], off
	global_load_dwordx2 v[58:59], v[26:27], off
	v_lshl_add_u64 v[22:23], s[16:17], 0, v[22:23]
	global_load_dwordx4 v[24:27], v[20:21], off
	global_load_dwordx2 v[68:69], v[22:23], off
	v_lshl_add_u64 v[20:21], v[60:61], 0, v[116:117]
	v_lshlrev_b64 v[22:23], 1, v[20:21]
	v_lshl_add_u64 v[28:29], s[12:13], 0, v[22:23]
	global_load_dwordx2 v[54:55], v[28:29], off
	v_lshl_add_u64 v[28:29], s[24:25], 0, v[22:23]
	v_lshl_add_u64 v[20:21], v[20:21], 2, s[14:15]
	v_lshl_add_u64 v[46:47], s[26:27], 0, v[22:23]
	global_load_dwordx2 v[56:57], v[28:29], off
	global_load_dwordx2 v[52:53], v[46:47], off
	v_lshl_add_u64 v[28:29], s[16:17], 0, v[22:23]
	global_load_dwordx4 v[20:23], v[20:21], off
	s_nop 0
	global_load_dwordx2 v[62:63], v[28:29], off
	v_or_b32_e32 v28, s0, v146
	s_lshl_b32 s33, s6, 2
	v_cmp_eq_u32_e64 s[6:7], 0, v28
	s_lshl_b64 s[46:47], s[48:49], 11
	s_add_u32 s50, s3, s33
	s_addc_u32 s51, s34, 0
	s_waitcnt vmcnt(22)
	v_lshlrev_b32_e32 v28, 16, v30
	v_and_b32_e32 v29, 0xffff0000, v30
	v_lshlrev_b32_e32 v30, 16, v31
	v_and_b32_e32 v31, 0xffff0000, v31
	s_waitcnt vmcnt(18)
	v_lshlrev_b32_e32 v74, 16, v32
	v_and_b32_e32 v75, 0xffff0000, v32
	s_waitcnt vmcnt(15)
	v_lshlrev_b32_e32 v46, 16, v34
	v_and_b32_e32 v47, 0xffff0000, v34
	v_lshlrev_b32_e32 v48, 16, v35
	v_and_b32_e32 v49, 0xffff0000, v35
	v_lshlrev_b32_e32 v32, 16, v33
	v_and_b32_e32 v33, 0xffff0000, v33
	v_pk_add_f32 v[34:35], v[48:49], -1.0 op_sel_hi:[1,0]
	v_pk_add_f32 v[72:73], v[46:47], -1.0 op_sel_hi:[1,0]
	v_pk_mul_f32 v[50:51], v[2:3], v[32:33]
	v_pk_mul_f32 v[70:71], v[0:1], v[74:75]
	v_pk_fma_f32 v[80:81], v[4:5], v[72:73], 1.0 op_sel_hi:[1,1,0]
	v_pk_fma_f32 v[34:35], v[6:7], v[34:35], 1.0 op_sel_hi:[1,1,0]
	v_pk_mul_f32 v[76:77], v[50:51], v[50:51]
	v_pk_mul_f32 v[78:79], v[70:71], v[70:71]
	v_pk_mul_f32 v[34:35], v[34:35], v[32:33]
	v_pk_mul_f32 v[32:33], v[80:81], v[74:75]
	v_pk_mov_b32 v[72:73], v[78:79], v[76:77] op_sel:[1,0]
	v_mov_b32_e32 v79, v77
	v_pk_mul_f32 v[74:75], v[32:33], v[28:29]
	v_pk_mul_f32 v[76:77], v[34:35], v[30:31]
	v_pk_mul_f32 v[74:75], v[8:9], v[74:75]
	v_pk_mul_f32 v[76:77], v[10:11], v[76:77]
	v_pk_add_f32 v[72:73], v[72:73], v[78:79]
	v_add_f32_e32 v74, v74, v75
	v_add_f32_e32 v75, v76, v77
	v_add_f32_e32 v72, v72, v73
	v_add_f32_e32 v74, v74, v75
	s_nop 0
	v_add_f32_dpp v72, v72, v72 quad_perm:[1,0,3,2] row_mask:0xf bank_mask:0xf bound_ctrl:1
	v_add_f32_dpp v74, v74, v74 quad_perm:[1,0,3,2] row_mask:0xf bank_mask:0xf bound_ctrl:1
	s_nop 0
	v_add_f32_dpp v72, v72, v72 quad_perm:[2,3,0,1] row_mask:0xf bank_mask:0xf bound_ctrl:1
	v_add_f32_dpp v74, v74, v74 quad_perm:[2,3,0,1] row_mask:0xf bank_mask:0xf bound_ctrl:1
	s_nop 0
	v_add_f32_dpp v72, v72, v72 row_half_mirror row_mask:0xf bank_mask:0xf bound_ctrl:1
	v_add_f32_dpp v74, v74, v74 row_half_mirror row_mask:0xf bank_mask:0xf bound_ctrl:1
	s_nop 0
	v_mov_b32_dpp v73, v72 row_mirror row_mask:0xf bank_mask:0xf bound_ctrl:1
	v_mov_b32_dpp v75, v74 row_mirror row_mask:0xf bank_mask:0xf bound_ctrl:1
	s_and_saveexec_b64 s[8:9], s[6:7]
	s_cbranch_execz .LBB0_1760
	v_lshl_add_u64 v[76:77], s[46:47], 0, v[88:89]
	v_lshlrev_b64 v[76:77], 7, v[76:77]
	v_lshl_add_u64 v[76:77], s[50:51], 0, v[76:77]
	v_add_f32_e32 v74, v74, v75
	global_store_dword v[76:77], v74, off

; #define LAS __attribute__((address_space(3)))
; __device__ __forceinline__ void conv_proc(f32x4 (&v)[2][8], const float* gain, int K, int Kp, int Np, int ilv, bf16* WT, LAS float* scr, int item, int lane) {
;     const int nblk = Np / 64, kb = item / nblk, nb = item % nblk, k0 = 64 * kb, n0 = 64 * nb;
;     const int d0 = ilv ? (((n0 % ilv) >> 7) * 256 + (n0 / ilv) * 128 + ((n0 % ilv) & 127)) : n0;
;     const int kr = lane >> 3, n4 = lane & 7;
;     if (gain) {
; #pragma unroll
;         for (int i = 0; i < 8; ++i) { const int k = k0 + 8 * i + kr; const float g = k < K ? gain[k] : 0.f; v[0][i] *= g; v[1][i] *= g; } }
; __device__ __forceinline__ void rwkv_scan_phase(Frame& F, const bf16* RKV, const float* WAG, const bf16* AGB, const float* k_k, const float* k_a, const float* r_k, bf16* Y, float* BS, float* ST2) {
;     ...
;             for (int ci = 0; ci < NCH; ci += 2) {
;                 if (ci >= 1) ST_FLUSH(ci - 1);
;                 if (ci + 2 < NCH) ST_LOAD(RA, ci + 2);
;                 ST_PROC(RB, ci + 1);
;                 __syncthreads();
;                 ST_FLUSH(ci);
;                 if (ci + 3 < NCH) ST_LOAD(RB, ci + 3);
;                 if (ci + 2 < NCH) ST_PROC(RA, ci + 2);
;                 __syncthreads();
.LBB0_1786:
	s_cmp_lt_u32 s80, 5
	s_cbranch_scc1 .Lcsbp_adv
	s_cmp_eq_u32 s69, 0
	s_cbranch_scc1 .Lcsbp_adv
	v_mbcnt_lo_u32_b32 v243, -1, 0
	v_mbcnt_hi_u32_b32 v243, -1, v243
	s_sub_u32 s92, s80, 5
	s_mul_i32 s92, s92, 0x2100
	s_add_u32 s92, s92, 0x19200
	v_lshrrev_b32_e32 v241, 3, v243
	v_and_b32_e32 v242, 7, v243
	v_mul_u32_u24_e32 v243, 132, v241
	v_lshl_add_u32 v243, v242, 4, v243
	v_add_u32_e32 v238, s92, v243
	v_mul_u32_u24_e32 v243, 0x420, v242
	v_lshl_add_u32 v243, v241, 2, v243
	v_add_u32_e32 v239, s92, v243
	v_mul_lo_u32 v243, v241, s81
	v_lshl_add_u32 v240, v242, 4, v243
	s_cmp_eq_u32 s32, 1
	s_cbranch_scc0 .Lcsbp_w0
	s_waitcnt vmcnt(10)
	s_branch .Lcsbp_wd

; __device__ __forceinline__ void conv_proc(f32x4 (&v)[2][8], const float* gain, int K, int Kp, int Np, int ilv, bf16* WT, LAS float* scr, int item, int lane) {
;     ...
;     if (gain) {
; #pragma unroll
;         for (int i = 0; i < 8; ++i) { const int k = k0 + 8 * i + kr; const float g = k < K ? gain[k] : 0.f; v[0][i] *= g; v[1][i] *= g; } }
.Lcsbp_wd:
	s_cmp_eq_u32 s71, 0
	s_cbranch_scc1 .Lcsbp_nogain
	v_pk_mul_f32 v[188:189], v[188:189], v[220:221] op_sel_hi:[1,0]
	v_pk_mul_f32 v[190:191], v[190:191], v[220:221] op_sel_hi:[1,0]
	v_pk_mul_f32 v[192:193], v[192:193], v[220:221] op_sel:[0,1] op_sel_hi:[1,1]
	v_pk_mul_f32 v[194:195], v[194:195], v[220:221] op_sel:[0,1] op_sel_hi:[1,1]
	v_pk_mul_f32 v[196:197], v[196:197], v[222:223] op_sel_hi:[1,0]
	v_pk_mul_f32 v[198:199], v[198:199], v[222:223] op_sel_hi:[1,0]
	v_pk_mul_f32 v[200:201], v[200:201], v[222:223] op_sel:[0,1] op_sel_hi:[1,1]
	v_pk_mul_f32 v[202:203], v[202:203], v[222:223] op_sel:[0,1] op_sel_hi:[1,1]
	v_pk_mul_f32 v[204:205], v[204:205], v[224:225] op_sel_hi:[1,0]
	v_pk_mul_f32 v[206:207], v[206:207], v[224:225] op_sel_hi:[1,0]
	v_pk_mul_f32 v[208:209], v[208:209], v[224:225] op_sel:[0,1] op_sel_hi:[1,1]
	v_pk_mul_f32 v[210:211], v[210:211], v[224:225] op_sel:[0,1] op_sel_hi:[1,1]
	v_pk_mul_f32 v[212:213], v[212:213], v[226:227] op_sel_hi:[1,0]
	v_pk_mul_f32 v[214:215], v[214:215], v[226:227] op_sel_hi:[1,0]
	v_pk_mul_f32 v[216:217], v[216:217], v[226:227] op_sel:[0,1] op_sel_hi:[1,1]
	v_pk_mul_f32 v[218:219], v[218:219], v[226:227] op_sel:[0,1] op_sel_hi:[1,1]

; __device__ __forceinline__ void convert_mats(Frame& F, int m_lo, int m_hi, int gw, int NGW) {
;     ...
;         while (it < base + cnt) {
;             f32x4 va[2][8], vb[2][8];
;             const int lim = base + cnt, i1 = it + NGW;
;             conv_load(src, mt.K, mt.N, mt.Np, it - base, F.lane, va);
;             if (i1 < lim) conv_load(src, mt.K, mt.N, mt.Np, i1 - base, F.lane, vb);
;             conv_proc(va, gain, mt.K, mt.Kp, mt.Np, mt.ilv, dst, scr, it - base, F.lane);
;             if (i1 < lim) conv_proc(vb, gain, mt.K, mt.Kp, mt.Np, mt.ilv, dst, scr, i1 - base, F.lane);
;             it = (i1 < lim) ? i1 + NGW : i1;
.Lcsbp_adv:
	s_mov_b32 s32, 0
	s_cmp_lt_u32 s80, 5
	s_cbranch_scc1 .Lcsb_end
	s_cmp_eq_u32 s66, 0
	s_cbranch_scc0 .Lcsb_nexttile
	s_mov_b32 s66, 1
	s_branch .Lcsb_find

; __device__ __forceinline__ void rwkv_scan_phase(Frame& F, const bf16* RKV, const float* WAG, const bf16* AGB, const float* k_k, const float* k_a, const float* r_k, bf16* Y, float* BS, float* ST2) {
;     ...
;                 if (ci + 2 < NCH) ST_LOAD(RA, ci + 2);
.LBB0_1789:
	s_or_b64 exec, exec, s[48:49]
	s_cmp_lt_u32 s58, 62
	s_cselect_b64 s[50:51], -1, 0
	s_cmp_gt_u32 s58, 61
	s_cselect_b64 s[48:49], -1, 0
	s_and_b64 vcc, exec, s[48:49]
	v_lshl_add_u64 v[80:81], s[10:11], 0, v[68:69]
	v_lshl_add_u64 v[82:83], s[10:11], 0, v[70:71]
	s_cbranch_vccnz .LBB0_1791
	s_mov_b32 s32, 1
	v_add_co_u32_e32 v12, vcc, 0x3c580000, v80
	s_nop 1
	v_addc_co_u32_e32 v13, vcc, 0, v81, vcc
	v_add_co_u32_e32 v14, vcc, 0x3e580000, v80
	s_nop 1
	v_addc_co_u32_e32 v15, vcc, 0, v81, vcc
	v_add_co_u32_e32 v16, vcc, 0x40580000, v80
	s_nop 1
	v_addc_co_u32_e32 v17, vcc, 0, v81, vcc
	global_load_dwordx2 v[36:37], v[12:13], off
	global_load_dwordx2 v[38:39], v[14:15], off
	global_load_dwordx2 v[40:41], v[16:17], off
	v_add_co_u32_e32 v12, vcc, 0x30600000, v82
	s_nop 1
	v_addc_co_u32_e32 v13, vcc, 0, v83, vcc
	v_add_co_u32_e32 v16, vcc, 0x34580000, v80
	s_nop 1
	v_addc_co_u32_e32 v17, vcc, 0, v81, vcc
	global_load_dwordx4 v[12:15], v[12:13], off
	s_nop 0
	global_load_dwordx2 v[42:43], v[16:17], off
	v_add_co_u32_e32 v16, vcc, 0x3c590000, v80
	s_nop 1
	v_addc_co_u32_e32 v17, vcc, 0, v81, vcc
	v_add_co_u32_e32 v18, vcc, 0x3e590000, v80
	s_nop 1
	v_addc_co_u32_e32 v19, vcc, 0, v81, vcc
	v_add_co_u32_e32 v28, vcc, 0x40590000, v80
	s_nop 1
	v_addc_co_u32_e32 v29, vcc, 0, v81, vcc
	global_load_dwordx2 v[44:45], v[16:17], off
	global_load_dwordx2 v[46:47], v[18:19], off
	global_load_dwordx2 v[48:49], v[28:29], off
	v_add_co_u32_e32 v16, vcc, 0x30620000, v82
	s_nop 1
	v_addc_co_u32_e32 v17, vcc, 0, v83, vcc
	v_add_co_u32_e32 v28, vcc, 0x34590000, v80
	s_nop 1
	v_addc_co_u32_e32 v29, vcc, 0, v81, vcc
	global_load_dwordx4 v[16:19], v[16:17], off
	s_nop 0
	global_load_dwordx2 v[50:51], v[28:29], off

; #define LAS __attribute__((address_space(3)))
; __device__ __forceinline__ void conv_proc(f32x4 (&v)[2][8], const float* gain, int K, int Kp, int Np, int ilv, bf16* WT, LAS float* scr, int item, int lane) {
;     const int nblk = Np / 64, kb = item / nblk, nb = item % nblk, k0 = 64 * kb, n0 = 64 * nb;
;     const int d0 = ilv ? (((n0 % ilv) >> 7) * 256 + (n0 / ilv) * 128 + ((n0 % ilv) & 127)) : n0;
;     const int kr = lane >> 3, n4 = lane & 7;
;     if (gain) {
; #pragma unroll
;         for (int i = 0; i < 8; ++i) { const int k = k0 + 8 * i + kr; const float g = k < K ? gain[k] : 0.f; v[0][i] *= g; v[1][i] *= g; } }
.LBB0_1797:
	s_or_b64 exec, exec, s[60:61]
	v_add_f32_e32 v181, v181, v182
	v_rsq_f32_e32 v181, v181
	ds_write_b128 v172, v[28:31] offset:45056
	ds_write_b128 v172, v[24:27] offset:53248
	ds_write_b128 v172, v[32:35] offset:61440
	v_max_f32_e64 v28, -v181, s35
	v_pk_mul_f32 v[30:31], v[142:143], v[28:29] op_sel_hi:[1,0]
	v_pk_mul_f32 v[28:29], v[144:145], v[28:29] op_sel_hi:[1,0]
	ds_write_b128 v178, v[28:31]
	v_pk_mul_f32 v[30:31], v[30:31], v[140:141] neg_lo:[1,0] neg_hi:[1,0]
	v_pk_mul_f32 v[28:29], v[28:29], v[138:139] neg_lo:[1,0] neg_hi:[1,0]
	ds_write_b128 v179, v[28:31]
	s_and_saveexec_b64 s[60:61], s[8:9]
	v_lshlrev_b32_e32 v28, 16, v64
	v_and_b32_e32 v29, 0xffff0000, v64
	v_lshlrev_b32_e32 v30, 16, v65
	v_and_b32_e32 v31, 0xffff0000, v65
	ds_write_b128 v180, v[28:31]
	s_or_b64 exec, exec, s[60:61]
	s_cmp_lt_u32 s80, 5
	s_cbranch_scc1 .Lcsap_adv
	s_cmp_eq_u32 s69, 0
	s_cbranch_scc1 .Lcsap_adv
	v_mbcnt_lo_u32_b32 v243, -1, 0
	v_mbcnt_hi_u32_b32 v243, -1, v243
	s_sub_u32 s92, s80, 5
	s_mul_i32 s92, s92, 0x2100
	s_add_u32 s92, s92, 0x19200
	v_lshrrev_b32_e32 v241, 3, v243
	v_and_b32_e32 v242, 7, v243
	v_mul_u32_u24_e32 v243, 132, v241
	v_lshl_add_u32 v243, v242, 4, v243
	v_add_u32_e32 v238, s92, v243
	v_mul_u32_u24_e32 v243, 0x420, v242
	v_lshl_add_u32 v243, v241, 2, v243
	v_add_u32_e32 v239, s92, v243
	v_mul_lo_u32 v243, v241, s81
	v_lshl_add_u32 v240, v242, 4, v243
	s_cmp_eq_u32 s32, 1
	s_cbranch_scc0 .Lcsap_w0
	s_waitcnt vmcnt(10)
	s_branch .Lcsap_wd

; __device__ __forceinline__ void rwkv_scan_phase(Frame& F, const bf16* RKV, const float* WAG, const bf16* AGB, const float* k_k, const float* k_a, const float* r_k, bf16* Y, float* BS, float* ST2) {
;     ...
;                 __syncthreads();
;                 ST_FLUSH(ci);
.Lcsa_end:
	s_waitcnt lgkmcnt(0)
	s_barrier
	ds_read_b128 v[28:31], v168
	v_add_co_u32_e32 v34, vcc, 0x49140000, v86
	s_waitcnt lgkmcnt(0)
	v_cvt_pk_bf16_f32 v32, v28, v29
	v_cvt_pk_bf16_f32 v33, v30, v31
	v_mul_f32_e32 v139, v31, v31
	v_addc_co_u32_e32 v35, vcc, 0, v87, vcc
	global_store_dwordx2 v[34:35], v[32:33], off
	v_mul_f32_e32 v33, v28, v28
	v_mul_f32_e32 v35, v29, v29
	v_mul_f32_e32 v87, v30, v30
	v_mov_b32_e32 v32, v28
	v_mov_b32_e32 v34, v29
	v_mov_b32_e32 v86, v30
	v_mov_b32_e32 v138, v31
	v_pk_add_f32 v[28:29], v[32:33], v[34:35]
	v_pk_add_f32 v[30:31], v[86:87], v[138:139]
	s_nop 0
	v_pk_add_f32 v[28:29], v[28:29], v[30:31]
	s_nop 1
	v_mov_b32_dpp v30, v28 quad_perm:[1,0,3,2] row_mask:0xf bank_mask:0xf bound_ctrl:1
	v_mov_b32_dpp v31, v29 quad_perm:[1,0,3,2] row_mask:0xf bank_mask:0xf bound_ctrl:1
	v_pk_add_f32 v[28:29], v[28:29], v[30:31]
	s_nop 1
	v_mov_b32_dpp v30, v28 quad_perm:[2,3,0,1] row_mask:0xf bank_mask:0xf bound_ctrl:1
	v_mov_b32_dpp v31, v29 quad_perm:[2,3,0,1] row_mask:0xf bank_mask:0xf bound_ctrl:1
	v_pk_add_f32 v[28:29], v[28:29], v[30:31]
	s_nop 1
	v_mov_b32_dpp v30, v28 row_half_mirror row_mask:0xf bank_mask:0xf bound_ctrl:1
	v_mov_b32_dpp v31, v29 row_half_mirror row_mask:0xf bank_mask:0xf bound_ctrl:1
	s_and_saveexec_b64 s[60:61], s[4:5]
	s_cbranch_execz .LBB0_1802
	v_pk_add_f32 v[28:29], v[28:29], v[30:31]
	v_add_co_u32_e32 v30, vcc, 0x48708000, v84
	s_nop 1
	v_addc_co_u32_e32 v31, vcc, 0, v85, vcc
	global_store_dwordx2 v[30:31], v[28:29], off
	s_or_b64 exec, exec, s[60:61]
	s_cmp_gt_u32 s58, 60
	s_cbranch_scc0 .LBB0_1803

; __device__ __forceinline__ void rwkv_scan_phase(Frame& F, const bf16* RKV, const float* WAG, const bf16* AGB, const float* k_k, const float* k_a, const float* r_k, bf16* Y, float* BS, float* ST2) {
;     ...
;                 if (ci + 3 < NCH) ST_LOAD(RB, ci + 3);
.LBB0_1803:
	s_mov_b32 s32, 1
	v_add_co_u32_e32 v20, vcc, 0x3c5a0000, v80
	s_nop 1
	v_addc_co_u32_e32 v21, vcc, 0, v81, vcc
	v_add_co_u32_e32 v22, vcc, 0x3e5a0000, v80
	s_nop 1
	v_addc_co_u32_e32 v23, vcc, 0, v81, vcc
	v_add_co_u32_e32 v24, vcc, 0x405a0000, v80
	s_nop 1
	v_addc_co_u32_e32 v25, vcc, 0, v81, vcc
	global_load_dwordx2 v[52:53], v[20:21], off
	global_load_dwordx2 v[54:55], v[22:23], off
	global_load_dwordx2 v[56:57], v[24:25], off
	v_add_co_u32_e32 v20, vcc, 0x30640000, v82
	s_nop 1
	v_addc_co_u32_e32 v21, vcc, 0, v83, vcc
	v_add_co_u32_e32 v24, vcc, 0x345a0000, v80
	s_nop 1
	v_addc_co_u32_e32 v25, vcc, 0, v81, vcc
	global_load_dwordx4 v[20:23], v[20:21], off
	s_nop 0
	global_load_dwordx2 v[58:59], v[24:25], off
	v_add_co_u32_e32 v24, vcc, 0x3c5b0000, v80
	s_nop 1
	v_addc_co_u32_e32 v25, vcc, 0, v81, vcc
	v_add_co_u32_e32 v26, vcc, 0x3e5b0000, v80
	s_nop 1
	v_addc_co_u32_e32 v27, vcc, 0, v81, vcc
	v_add_co_u32_e32 v28, vcc, 0x405b0000, v80
	s_nop 1
	v_addc_co_u32_e32 v29, vcc, 0, v81, vcc
	global_load_dwordx2 v[60:61], v[24:25], off
	global_load_dwordx2 v[62:63], v[26:27], off
	global_load_dwordx2 v[64:65], v[28:29], off
	v_add_co_u32_e32 v24, vcc, 0x30660000, v82
	s_nop 1
	v_addc_co_u32_e32 v25, vcc, 0, v83, vcc
	v_add_co_u32_e32 v28, vcc, 0x345b0000, v80
	s_nop 1
	v_addc_co_u32_e32 v29, vcc, 0, v81, vcc
	global_load_dwordx4 v[24:27], v[24:25], off
	s_nop 0
	global_load_dwordx2 v[66:67], v[28:29], off
	s_andn2_b64 vcc, exec, s[50:51]
	s_cbranch_vccnz .LBB0_1786

; __device__ __forceinline__ void convert_mats(Frame& F, int m_lo, int m_hi, int gw, int NGW) {
;     ...
;         while (it < base + cnt) {
;             f32x4 va[2][8], vb[2][8];
;             const int lim = base + cnt, i1 = it + NGW;
;             conv_load(src, mt.K, mt.N, mt.Np, it - base, F.lane, va);
;             if (i1 < lim) conv_load(src, mt.K, mt.N, mt.Np, i1 - base, F.lane, vb);
;             conv_proc(va, gain, mt.K, mt.Kp, mt.Np, mt.ilv, dst, scr, it - base, F.lane);
;             if (i1 < lim) conv_proc(vb, gain, mt.K, mt.Kp, mt.Np, mt.ilv, dst, scr, i1 - base, F.lane);
;             it = (i1 < lim) ? i1 + NGW : i1;
.Lcsdp_adv:
	s_mov_b32 s32, 0
	s_cmp_eq_u32 s66, 0
	s_cbranch_scc0 .Lcsd_nexttile
	s_mov_b32 s66, 1
	s_branch .Lcsd_find
